# hand-written S5 carry scan: each wave loads its 64 sub-chunk end states once (all in flight), scans from registers, 8-wave carry through LDS, replays for the h_in stores
# speedup vs baseline: 1.0297x; 1.0029x over previous
; __device__ __forceinline__ float bf_lo(unsigned w) { return __uint_as_float(w << 16); }
; __device__ __forceinline__ float bf_hi(unsigned w) { return __uint_as_float(w & 0xffff0000u); }
; __device__ __forceinline__ f32x2 cmul(f32x2 a, f32x2 b) { return (f32x2){a.x * b.x - a.y * b.y, a.x * b.y + a.y * b.x}; }
; __device__ __forceinline__ void phase_scan(const Args& a, LAS unsigned char* lds, int l, int G, const int bid, const int tid) {
;     ...
;     for (int pair = bid; pair < PB_ * NG; pair += G) {
;         const int seq = pair / NG, g = pair % NG;
;         const f32x2 lam = aux[(l * NG + g) * NP + p], lseg = aux[2 * NG * NP + (l * NG + g) * NP + p];
;         const int j0 = seq * (PL / TS) + wave * 64;
;         const unsigned* ep = (const unsigned*)(E + ((size_t)g * NJ + j0) * 128) + p;
;         f32x2 h = {0.f, 0.f};
;         for (int i0 = 0; i0 < 64; i0 += 16) { unsigned eb[16];
; #pragma unroll
;             for (int k = 0; k < 16; ++k) eb[k] = ep[(size_t)(i0 + k) * 64];
; #pragma unroll
;             for (int k = 0; k < 16; ++k) h = cmul(lam, h) + (f32x2){pg8::bf_lo(eb[k]), pg8::bf_hi(eb[k])}; }
;         sL[wave * 64 + p] = h;
.Lscan_next:
	s_add_i32 s12, s12, s33
	s_cmpk_gt_i32 s12, 0xff
	s_barrier
	s_cbranch_scc1 .LBB0_489
.LBB0_480:
.Lscan_pair:
	v_readfirstlane_b32 s0, v1
	s_lshr_b32 s13, s12, 5
	s_and_b32 s14, s12, 31
	v_readlane_b32 s8, v253, 20
	v_readlane_b32 s9, v253, 21
	v_readlane_b32 s16, v253, 16
	v_readlane_b32 s17, v253, 17
	v_lshlrev_b32_e32 v22, 2, v0
	v_lshlrev_b32_e32 v23, 3, v0
	s_nop 1
	s_sub_u32 s52, s16, 0x6600000
	s_subb_u32 s53, s17, 0
	s_lshl_b32 s1, s14, 6
	s_add_u32 s1, s1, s10
	s_lshl_b32 s1, s1, 3
	s_add_u32 s8, s8, s1
	s_addc_u32 s9, s9, 0
	global_load_dwordx2 v[8:9], v23, s[8:9]
	s_add_u32 s8, s8, 0x8000
	s_addc_u32 s9, s9, 0
	global_load_dwordx2 v[10:11], v23, s[8:9]
	s_lshl_b32 s54, s13, 9
	s_lshl_b32 s55, s0, 6
	s_add_u32 s54, s54, s55
	s_mul_i32 s55, s14, 0x1080
	s_add_u32 s55, s55, s54
	s_add_u32 s55, s55, 16
	s_lshl_b32 s55, s55, 8
	s_add_u32 s16, s16, s55
	s_addc_u32 s17, s17, 0
	global_load_dword v64, v22, s[16:17] offset:-4096
	global_load_dword v65, v22, s[16:17] offset:-3840
	global_load_dword v66, v22, s[16:17] offset:-3584
	global_load_dword v67, v22, s[16:17] offset:-3328
	global_load_dword v68, v22, s[16:17] offset:-3072
	global_load_dword v69, v22, s[16:17] offset:-2816
	global_load_dword v70, v22, s[16:17] offset:-2560
	global_load_dword v71, v22, s[16:17] offset:-2304
	global_load_dword v72, v22, s[16:17] offset:-2048
	global_load_dword v73, v22, s[16:17] offset:-1792
	global_load_dword v74, v22, s[16:17] offset:-1536
	global_load_dword v75, v22, s[16:17] offset:-1280
	global_load_dword v76, v22, s[16:17] offset:-1024
	global_load_dword v77, v22, s[16:17] offset:-768
	global_load_dword v78, v22, s[16:17] offset:-512
	global_load_dword v79, v22, s[16:17] offset:-256
	global_load_dword v80, v22, s[16:17] offset:0
	global_load_dword v81, v22, s[16:17] offset:256
	global_load_dword v82, v22, s[16:17] offset:512
	global_load_dword v83, v22, s[16:17] offset:768
	global_load_dword v84, v22, s[16:17] offset:1024
	global_load_dword v85, v22, s[16:17] offset:1280
	global_load_dword v86, v22, s[16:17] offset:1536
	global_load_dword v87, v22, s[16:17] offset:1792
	global_load_dword v88, v22, s[16:17] offset:2048
	global_load_dword v89, v22, s[16:17] offset:2304
	global_load_dword v90, v22, s[16:17] offset:2560
	global_load_dword v91, v22, s[16:17] offset:2816
	global_load_dword v92, v22, s[16:17] offset:3072
	global_load_dword v93, v22, s[16:17] offset:3328
	global_load_dword v94, v22, s[16:17] offset:3584
	global_load_dword v95, v22, s[16:17] offset:3840
	s_waitcnt vmcnt(30)
	s_add_u32 s16, s16, 0x2000
	s_addc_u32 s17, s17, 0
	global_load_dword v96, v22, s[16:17] offset:-4096
	global_load_dword v97, v22, s[16:17] offset:-3840
	global_load_dword v98, v22, s[16:17] offset:-3584
	global_load_dword v99, v22, s[16:17] offset:-3328
	global_load_dword v100, v22, s[16:17] offset:-3072
	global_load_dword v101, v22, s[16:17] offset:-2816
	global_load_dword v102, v22, s[16:17] offset:-2560
	global_load_dword v103, v22, s[16:17] offset:-2304
	global_load_dword v104, v22, s[16:17] offset:-2048
	global_load_dword v105, v22, s[16:17] offset:-1792
	global_load_dword v106, v22, s[16:17] offset:-1536
	global_load_dword v107, v22, s[16:17] offset:-1280
	global_load_dword v108, v22, s[16:17] offset:-1024
	global_load_dword v109, v22, s[16:17] offset:-768
	global_load_dword v110, v22, s[16:17] offset:-512
	global_load_dword v111, v22, s[16:17] offset:-256
	global_load_dword v112, v22, s[16:17] offset:0
	global_load_dword v113, v22, s[16:17] offset:256
	global_load_dword v114, v22, s[16:17] offset:512
	global_load_dword v115, v22, s[16:17] offset:768
	global_load_dword v116, v22, s[16:17] offset:1024
	global_load_dword v117, v22, s[16:17] offset:1280
	global_load_dword v118, v22, s[16:17] offset:1536
	global_load_dword v119, v22, s[16:17] offset:1792
	global_load_dword v120, v22, s[16:17] offset:2048
	global_load_dword v121, v22, s[16:17] offset:2304
	global_load_dword v122, v22, s[16:17] offset:2560
	global_load_dword v123, v22, s[16:17] offset:2816
	global_load_dword v124, v22, s[16:17] offset:3072
	global_load_dword v125, v22, s[16:17] offset:3328
	global_load_dword v126, v22, s[16:17] offset:3584
	global_load_dword v127, v22, s[16:17] offset:3840
	s_lshr_b32 s55, s14, 1
	s_mul_i32 s55, s55, 0x1100
	s_add_u32 s55, s55, s54
	s_mul_i32 s56, s55, 0x600
	s_mul_hi_u32 s57, s55, 0x600
	s_add_u32 s52, s52, s56
	s_addc_u32 s53, s53, s57
	s_and_b32 s55, s14, 1
	s_mul_i32 s55, s55, 0x300
	s_add_u32 s55, s55, 0x200
	s_add_u32 s52, s52, s55
	s_addc_u32 s53, s53, 0
	v_mov_b32_e32 v12, 0
	v_mov_b32_e32 v13, 0
	s_waitcnt vmcnt(0)
; __device__ __forceinline__ float bf_lo(unsigned w) { return __uint_as_float(w << 16); }
; __device__ __forceinline__ float bf_hi(unsigned w) { return __uint_as_float(w & 0xffff0000u); }
; __device__ __forceinline__ f32x2 cmul(f32x2 a, f32x2 b) { return (f32x2){a.x * b.x - a.y * b.y, a.x * b.y + a.y * b.x}; }
; __device__ __forceinline__ void phase_scan(const Args& a, LAS unsigned char* lds, int l, int G, const int bid, const int tid) {
;     ...
;         for (int i0 = 0; i0 < 64; i0 += 16) { unsigned eb[16];
; #pragma unroll
;             for (int k = 0; k < 16; ++k) eb[k] = ep[(size_t)(i0 + k) * 64];
; #pragma unroll
;             for (int k = 0; k < 16; ++k) h = cmul(lam, h) + (f32x2){pg8::bf_lo(eb[k]), pg8::bf_hi(eb[k])}; }
	v_lshlrev_b32_e32 v16, 16, v64
	v_and_b32_e32 v17, 0xffff0000, v64
	v_fma_f32 v14, v8, v12, v16
	v_fma_f32 v15, v8, v13, v17
	v_fma_f32 v14, -v9, v13, v14
	v_fma_f32 v13, v9, v12, v15
	v_mov_b32_e32 v12, v14
	v_lshlrev_b32_e32 v16, 16, v65
	v_and_b32_e32 v17, 0xffff0000, v65
	v_fma_f32 v14, v8, v12, v16
	v_fma_f32 v15, v8, v13, v17
	v_fma_f32 v14, -v9, v13, v14
	v_fma_f32 v13, v9, v12, v15
	v_mov_b32_e32 v12, v14
	v_lshlrev_b32_e32 v16, 16, v66
	v_and_b32_e32 v17, 0xffff0000, v66
	v_fma_f32 v14, v8, v12, v16
	v_fma_f32 v15, v8, v13, v17
	v_fma_f32 v14, -v9, v13, v14
	v_fma_f32 v13, v9, v12, v15
	v_mov_b32_e32 v12, v14
	v_lshlrev_b32_e32 v16, 16, v67
	v_and_b32_e32 v17, 0xffff0000, v67
	v_fma_f32 v14, v8, v12, v16
	v_fma_f32 v15, v8, v13, v17
	v_fma_f32 v14, -v9, v13, v14
	v_fma_f32 v13, v9, v12, v15
	v_mov_b32_e32 v12, v14
	v_lshlrev_b32_e32 v16, 16, v68
	v_and_b32_e32 v17, 0xffff0000, v68
	v_fma_f32 v14, v8, v12, v16
	v_fma_f32 v15, v8, v13, v17
	v_fma_f32 v14, -v9, v13, v14
	v_fma_f32 v13, v9, v12, v15
	v_mov_b32_e32 v12, v14
	v_lshlrev_b32_e32 v16, 16, v69
	v_and_b32_e32 v17, 0xffff0000, v69
	v_fma_f32 v14, v8, v12, v16
	v_fma_f32 v15, v8, v13, v17
	v_fma_f32 v14, -v9, v13, v14
	v_fma_f32 v13, v9, v12, v15
	v_mov_b32_e32 v12, v14
	v_lshlrev_b32_e32 v16, 16, v70
	v_and_b32_e32 v17, 0xffff0000, v70
	v_fma_f32 v14, v8, v12, v16
	v_fma_f32 v15, v8, v13, v17
	v_fma_f32 v14, -v9, v13, v14
	v_fma_f32 v13, v9, v12, v15
	v_mov_b32_e32 v12, v14
	v_lshlrev_b32_e32 v16, 16, v71
	v_and_b32_e32 v17, 0xffff0000, v71
	v_fma_f32 v14, v8, v12, v16
	v_fma_f32 v15, v8, v13, v17
	v_fma_f32 v14, -v9, v13, v14
	v_fma_f32 v13, v9, v12, v15
	v_mov_b32_e32 v12, v14
	v_lshlrev_b32_e32 v16, 16, v72
	v_and_b32_e32 v17, 0xffff0000, v72
	v_fma_f32 v14, v8, v12, v16
	v_fma_f32 v15, v8, v13, v17
	v_fma_f32 v14, -v9, v13, v14
	v_fma_f32 v13, v9, v12, v15
	v_mov_b32_e32 v12, v14
	v_lshlrev_b32_e32 v16, 16, v73
	v_and_b32_e32 v17, 0xffff0000, v73
	v_fma_f32 v14, v8, v12, v16
	v_fma_f32 v15, v8, v13, v17
	v_fma_f32 v14, -v9, v13, v14
	v_fma_f32 v13, v9, v12, v15
	v_mov_b32_e32 v12, v14
	v_lshlrev_b32_e32 v16, 16, v74
	v_and_b32_e32 v17, 0xffff0000, v74
	v_fma_f32 v14, v8, v12, v16
	v_fma_f32 v15, v8, v13, v17
	v_fma_f32 v14, -v9, v13, v14
	v_fma_f32 v13, v9, v12, v15
	v_mov_b32_e32 v12, v14
	v_lshlrev_b32_e32 v16, 16, v75
	v_and_b32_e32 v17, 0xffff0000, v75
	v_fma_f32 v14, v8, v12, v16
	v_fma_f32 v15, v8, v13, v17
	v_fma_f32 v14, -v9, v13, v14
	v_fma_f32 v13, v9, v12, v15
	v_mov_b32_e32 v12, v14
	v_lshlrev_b32_e32 v16, 16, v76
	v_and_b32_e32 v17, 0xffff0000, v76
	v_fma_f32 v14, v8, v12, v16
	v_fma_f32 v15, v8, v13, v17
	v_fma_f32 v14, -v9, v13, v14
	v_fma_f32 v13, v9, v12, v15
	v_mov_b32_e32 v12, v14
	v_lshlrev_b32_e32 v16, 16, v77
	v_and_b32_e32 v17, 0xffff0000, v77
	v_fma_f32 v14, v8, v12, v16
	v_fma_f32 v15, v8, v13, v17
	v_fma_f32 v14, -v9, v13, v14
	v_fma_f32 v13, v9, v12, v15
	v_mov_b32_e32 v12, v14
	v_lshlrev_b32_e32 v16, 16, v78
	v_and_b32_e32 v17, 0xffff0000, v78
	v_fma_f32 v14, v8, v12, v16
	v_fma_f32 v15, v8, v13, v17
	v_fma_f32 v14, -v9, v13, v14
	v_fma_f32 v13, v9, v12, v15
	v_mov_b32_e32 v12, v14
	v_lshlrev_b32_e32 v16, 16, v79
	v_and_b32_e32 v17, 0xffff0000, v79
	v_fma_f32 v14, v8, v12, v16
	v_fma_f32 v15, v8, v13, v17
	v_fma_f32 v14, -v9, v13, v14
	v_fma_f32 v13, v9, v12, v15
	v_mov_b32_e32 v12, v14
	v_lshlrev_b32_e32 v16, 16, v80
	v_and_b32_e32 v17, 0xffff0000, v80
	v_fma_f32 v14, v8, v12, v16
	v_fma_f32 v15, v8, v13, v17
	v_fma_f32 v14, -v9, v13, v14
	v_fma_f32 v13, v9, v12, v15
	v_mov_b32_e32 v12, v14
	v_lshlrev_b32_e32 v16, 16, v81
	v_and_b32_e32 v17, 0xffff0000, v81
	v_fma_f32 v14, v8, v12, v16
	v_fma_f32 v15, v8, v13, v17
	v_fma_f32 v14, -v9, v13, v14
	v_fma_f32 v13, v9, v12, v15
	v_mov_b32_e32 v12, v14
	v_lshlrev_b32_e32 v16, 16, v82
	v_and_b32_e32 v17, 0xffff0000, v82
	v_fma_f32 v14, v8, v12, v16
	v_fma_f32 v15, v8, v13, v17
	v_fma_f32 v14, -v9, v13, v14
	v_fma_f32 v13, v9, v12, v15
	v_mov_b32_e32 v12, v14
	v_lshlrev_b32_e32 v16, 16, v83
	v_and_b32_e32 v17, 0xffff0000, v83
	v_fma_f32 v14, v8, v12, v16
	v_fma_f32 v15, v8, v13, v17
	v_fma_f32 v14, -v9, v13, v14
	v_fma_f32 v13, v9, v12, v15
	v_mov_b32_e32 v12, v14
	v_lshlrev_b32_e32 v16, 16, v84
	v_and_b32_e32 v17, 0xffff0000, v84
	v_fma_f32 v14, v8, v12, v16
	v_fma_f32 v15, v8, v13, v17
	v_fma_f32 v14, -v9, v13, v14
	v_fma_f32 v13, v9, v12, v15
	v_mov_b32_e32 v12, v14
	v_lshlrev_b32_e32 v16, 16, v85
	v_and_b32_e32 v17, 0xffff0000, v85
	v_fma_f32 v14, v8, v12, v16
	v_fma_f32 v15, v8, v13, v17
	v_fma_f32 v14, -v9, v13, v14
	v_fma_f32 v13, v9, v12, v15
	v_mov_b32_e32 v12, v14
	v_lshlrev_b32_e32 v16, 16, v86
	v_and_b32_e32 v17, 0xffff0000, v86
	v_fma_f32 v14, v8, v12, v16
	v_fma_f32 v15, v8, v13, v17
	v_fma_f32 v14, -v9, v13, v14
	v_fma_f32 v13, v9, v12, v15
	v_mov_b32_e32 v12, v14
	v_lshlrev_b32_e32 v16, 16, v87
	v_and_b32_e32 v17, 0xffff0000, v87
	v_fma_f32 v14, v8, v12, v16
	v_fma_f32 v15, v8, v13, v17
	v_fma_f32 v14, -v9, v13, v14
	v_fma_f32 v13, v9, v12, v15
	v_mov_b32_e32 v12, v14
	v_lshlrev_b32_e32 v16, 16, v88
	v_and_b32_e32 v17, 0xffff0000, v88
	v_fma_f32 v14, v8, v12, v16
	v_fma_f32 v15, v8, v13, v17
	v_fma_f32 v14, -v9, v13, v14
	v_fma_f32 v13, v9, v12, v15
	v_mov_b32_e32 v12, v14
	v_lshlrev_b32_e32 v16, 16, v89
	v_and_b32_e32 v17, 0xffff0000, v89
	v_fma_f32 v14, v8, v12, v16
	v_fma_f32 v15, v8, v13, v17
	v_fma_f32 v14, -v9, v13, v14
	v_fma_f32 v13, v9, v12, v15
	v_mov_b32_e32 v12, v14
	v_lshlrev_b32_e32 v16, 16, v90
	v_and_b32_e32 v17, 0xffff0000, v90
	v_fma_f32 v14, v8, v12, v16
	v_fma_f32 v15, v8, v13, v17
	v_fma_f32 v14, -v9, v13, v14
	v_fma_f32 v13, v9, v12, v15
	v_mov_b32_e32 v12, v14
; __device__ __forceinline__ float bf_lo(unsigned w) { return __uint_as_float(w << 16); }
; __device__ __forceinline__ float bf_hi(unsigned w) { return __uint_as_float(w & 0xffff0000u); }
; __device__ __forceinline__ f32x2 cmul(f32x2 a, f32x2 b) { return (f32x2){a.x * b.x - a.y * b.y, a.x * b.y + a.y * b.x}; }
; __device__ __forceinline__ void phase_scan(const Args& a, LAS unsigned char* lds, int l, int G, const int bid, const int tid) {
;     ...
;         for (int i0 = 0; i0 < 64; i0 += 16) { unsigned eb[16];
; #pragma unroll
;             for (int k = 0; k < 16; ++k) eb[k] = ep[(size_t)(i0 + k) * 64];
; #pragma unroll
;             for (int k = 0; k < 16; ++k) h = cmul(lam, h) + (f32x2){pg8::bf_lo(eb[k]), pg8::bf_hi(eb[k])}; }
	v_lshlrev_b32_e32 v16, 16, v91
	v_and_b32_e32 v17, 0xffff0000, v91
	v_fma_f32 v14, v8, v12, v16
	v_fma_f32 v15, v8, v13, v17
	v_fma_f32 v14, -v9, v13, v14
	v_fma_f32 v13, v9, v12, v15
	v_mov_b32_e32 v12, v14
	v_lshlrev_b32_e32 v16, 16, v92
	v_and_b32_e32 v17, 0xffff0000, v92
	v_fma_f32 v14, v8, v12, v16
	v_fma_f32 v15, v8, v13, v17
	v_fma_f32 v14, -v9, v13, v14
	v_fma_f32 v13, v9, v12, v15
	v_mov_b32_e32 v12, v14
	v_lshlrev_b32_e32 v16, 16, v93
	v_and_b32_e32 v17, 0xffff0000, v93
	v_fma_f32 v14, v8, v12, v16
	v_fma_f32 v15, v8, v13, v17
	v_fma_f32 v14, -v9, v13, v14
	v_fma_f32 v13, v9, v12, v15
	v_mov_b32_e32 v12, v14
	v_lshlrev_b32_e32 v16, 16, v94
	v_and_b32_e32 v17, 0xffff0000, v94
	v_fma_f32 v14, v8, v12, v16
	v_fma_f32 v15, v8, v13, v17
	v_fma_f32 v14, -v9, v13, v14
	v_fma_f32 v13, v9, v12, v15
	v_mov_b32_e32 v12, v14
	v_lshlrev_b32_e32 v16, 16, v95
	v_and_b32_e32 v17, 0xffff0000, v95
	v_fma_f32 v14, v8, v12, v16
	v_fma_f32 v15, v8, v13, v17
	v_fma_f32 v14, -v9, v13, v14
	v_fma_f32 v13, v9, v12, v15
	v_mov_b32_e32 v12, v14
	v_lshlrev_b32_e32 v16, 16, v96
	v_and_b32_e32 v17, 0xffff0000, v96
	v_fma_f32 v14, v8, v12, v16
	v_fma_f32 v15, v8, v13, v17
	v_fma_f32 v14, -v9, v13, v14
	v_fma_f32 v13, v9, v12, v15
	v_mov_b32_e32 v12, v14
	v_lshlrev_b32_e32 v16, 16, v97
	v_and_b32_e32 v17, 0xffff0000, v97
	v_fma_f32 v14, v8, v12, v16
	v_fma_f32 v15, v8, v13, v17
	v_fma_f32 v14, -v9, v13, v14
	v_fma_f32 v13, v9, v12, v15
	v_mov_b32_e32 v12, v14
	v_lshlrev_b32_e32 v16, 16, v98
	v_and_b32_e32 v17, 0xffff0000, v98
	v_fma_f32 v14, v8, v12, v16
	v_fma_f32 v15, v8, v13, v17
	v_fma_f32 v14, -v9, v13, v14
	v_fma_f32 v13, v9, v12, v15
	v_mov_b32_e32 v12, v14
	v_lshlrev_b32_e32 v16, 16, v99
	v_and_b32_e32 v17, 0xffff0000, v99
	v_fma_f32 v14, v8, v12, v16
	v_fma_f32 v15, v8, v13, v17
	v_fma_f32 v14, -v9, v13, v14
	v_fma_f32 v13, v9, v12, v15
	v_mov_b32_e32 v12, v14
	v_lshlrev_b32_e32 v16, 16, v100
	v_and_b32_e32 v17, 0xffff0000, v100
	v_fma_f32 v14, v8, v12, v16
	v_fma_f32 v15, v8, v13, v17
	v_fma_f32 v14, -v9, v13, v14
	v_fma_f32 v13, v9, v12, v15
	v_mov_b32_e32 v12, v14
	v_lshlrev_b32_e32 v16, 16, v101
	v_and_b32_e32 v17, 0xffff0000, v101
	v_fma_f32 v14, v8, v12, v16
	v_fma_f32 v15, v8, v13, v17
	v_fma_f32 v14, -v9, v13, v14
	v_fma_f32 v13, v9, v12, v15
	v_mov_b32_e32 v12, v14
	v_lshlrev_b32_e32 v16, 16, v102
	v_and_b32_e32 v17, 0xffff0000, v102
	v_fma_f32 v14, v8, v12, v16
	v_fma_f32 v15, v8, v13, v17
	v_fma_f32 v14, -v9, v13, v14
	v_fma_f32 v13, v9, v12, v15
	v_mov_b32_e32 v12, v14
	v_lshlrev_b32_e32 v16, 16, v103
	v_and_b32_e32 v17, 0xffff0000, v103
	v_fma_f32 v14, v8, v12, v16
	v_fma_f32 v15, v8, v13, v17
	v_fma_f32 v14, -v9, v13, v14
	v_fma_f32 v13, v9, v12, v15
	v_mov_b32_e32 v12, v14
	v_lshlrev_b32_e32 v16, 16, v104
	v_and_b32_e32 v17, 0xffff0000, v104
	v_fma_f32 v14, v8, v12, v16
	v_fma_f32 v15, v8, v13, v17
	v_fma_f32 v14, -v9, v13, v14
	v_fma_f32 v13, v9, v12, v15
	v_mov_b32_e32 v12, v14
	v_lshlrev_b32_e32 v16, 16, v105
	v_and_b32_e32 v17, 0xffff0000, v105
	v_fma_f32 v14, v8, v12, v16
	v_fma_f32 v15, v8, v13, v17
	v_fma_f32 v14, -v9, v13, v14
	v_fma_f32 v13, v9, v12, v15
	v_mov_b32_e32 v12, v14
	v_lshlrev_b32_e32 v16, 16, v106
	v_and_b32_e32 v17, 0xffff0000, v106
	v_fma_f32 v14, v8, v12, v16
	v_fma_f32 v15, v8, v13, v17
	v_fma_f32 v14, -v9, v13, v14
	v_fma_f32 v13, v9, v12, v15
	v_mov_b32_e32 v12, v14
	v_lshlrev_b32_e32 v16, 16, v107
	v_and_b32_e32 v17, 0xffff0000, v107
	v_fma_f32 v14, v8, v12, v16
	v_fma_f32 v15, v8, v13, v17
	v_fma_f32 v14, -v9, v13, v14
	v_fma_f32 v13, v9, v12, v15
	v_mov_b32_e32 v12, v14
	v_lshlrev_b32_e32 v16, 16, v108
	v_and_b32_e32 v17, 0xffff0000, v108
	v_fma_f32 v14, v8, v12, v16
	v_fma_f32 v15, v8, v13, v17
	v_fma_f32 v14, -v9, v13, v14
	v_fma_f32 v13, v9, v12, v15
	v_mov_b32_e32 v12, v14
	v_lshlrev_b32_e32 v16, 16, v109
	v_and_b32_e32 v17, 0xffff0000, v109
	v_fma_f32 v14, v8, v12, v16
	v_fma_f32 v15, v8, v13, v17
	v_fma_f32 v14, -v9, v13, v14
	v_fma_f32 v13, v9, v12, v15
	v_mov_b32_e32 v12, v14
	v_lshlrev_b32_e32 v16, 16, v110
	v_and_b32_e32 v17, 0xffff0000, v110
	v_fma_f32 v14, v8, v12, v16
	v_fma_f32 v15, v8, v13, v17
	v_fma_f32 v14, -v9, v13, v14
	v_fma_f32 v13, v9, v12, v15
	v_mov_b32_e32 v12, v14
	v_lshlrev_b32_e32 v16, 16, v111
	v_and_b32_e32 v17, 0xffff0000, v111
	v_fma_f32 v14, v8, v12, v16
	v_fma_f32 v15, v8, v13, v17
	v_fma_f32 v14, -v9, v13, v14
	v_fma_f32 v13, v9, v12, v15
	v_mov_b32_e32 v12, v14
	v_lshlrev_b32_e32 v16, 16, v112
	v_and_b32_e32 v17, 0xffff0000, v112
	v_fma_f32 v14, v8, v12, v16
	v_fma_f32 v15, v8, v13, v17
	v_fma_f32 v14, -v9, v13, v14
	v_fma_f32 v13, v9, v12, v15
	v_mov_b32_e32 v12, v14
	v_lshlrev_b32_e32 v16, 16, v113
	v_and_b32_e32 v17, 0xffff0000, v113
	v_fma_f32 v14, v8, v12, v16
	v_fma_f32 v15, v8, v13, v17
	v_fma_f32 v14, -v9, v13, v14
	v_fma_f32 v13, v9, v12, v15
	v_mov_b32_e32 v12, v14
	v_lshlrev_b32_e32 v16, 16, v114
	v_and_b32_e32 v17, 0xffff0000, v114
	v_fma_f32 v14, v8, v12, v16
	v_fma_f32 v15, v8, v13, v17
	v_fma_f32 v14, -v9, v13, v14
	v_fma_f32 v13, v9, v12, v15
	v_mov_b32_e32 v12, v14
	v_lshlrev_b32_e32 v16, 16, v115
	v_and_b32_e32 v17, 0xffff0000, v115
	v_fma_f32 v14, v8, v12, v16
	v_fma_f32 v15, v8, v13, v17
	v_fma_f32 v14, -v9, v13, v14
	v_fma_f32 v13, v9, v12, v15
	v_mov_b32_e32 v12, v14
	v_lshlrev_b32_e32 v16, 16, v116
	v_and_b32_e32 v17, 0xffff0000, v116
	v_fma_f32 v14, v8, v12, v16
	v_fma_f32 v15, v8, v13, v17
	v_fma_f32 v14, -v9, v13, v14
	v_fma_f32 v13, v9, v12, v15
	v_mov_b32_e32 v12, v14
	v_lshlrev_b32_e32 v16, 16, v117
	v_and_b32_e32 v17, 0xffff0000, v117
	v_fma_f32 v14, v8, v12, v16
	v_fma_f32 v15, v8, v13, v17
	v_fma_f32 v14, -v9, v13, v14
; __device__ __forceinline__ float bf_lo(unsigned w) { return __uint_as_float(w << 16); }
; __device__ __forceinline__ float bf_hi(unsigned w) { return __uint_as_float(w & 0xffff0000u); }
; __device__ __forceinline__ unsigned pk2(float lo, float hi) { return pg8::cvt_pk_bf16(lo, hi); }
; __device__ __forceinline__ f32x2 cmul(f32x2 a, f32x2 b) { return (f32x2){a.x * b.x - a.y * b.y, a.x * b.y + a.y * b.x}; }
; __device__ __forceinline__ void phase_scan(const Args& a, LAS unsigned char* lds, int l, int G, const int bid, const int tid) {
;     ...
;             for (int k = 0; k < 16; ++k) h = cmul(lam, h) + (f32x2){pg8::bf_lo(eb[k]), pg8::bf_hi(eb[k])}; }
;         sL[wave * 64 + p] = h;
;         __syncthreads();
;         f32x2 c = {0.f, 0.f};
;         for (int w2 = 0; w2 < wave; ++w2) c = cmul(lseg, c) + sL[w2 * 64 + p];
;         h = c;
;         unsigned* hp = (unsigned*)(AB + ((size_t)((g >> 1) * NJP + j0) * ABP + (g & 1) * 384 + 256 + 2 * p));
;         for (int i0 = 0; i0 < 64; i0 += 16) { unsigned eb[16];
; #pragma unroll
;             for (int k = 0; k < 16; ++k) eb[k] = ep[(size_t)(i0 + k) * 64];
; #pragma unroll
;             for (int k = 0; k < 16; ++k) { hp[(size_t)(i0 + k) * (ABP / 2)] = pk2(h.x, h.y); h = cmul(lam, h) + (f32x2){pg8::bf_lo(eb[k]), pg8::bf_hi(eb[k])}; } }
	v_fma_f32 v13, v9, v12, v15
	v_mov_b32_e32 v12, v14
	v_lshlrev_b32_e32 v16, 16, v118
	v_and_b32_e32 v17, 0xffff0000, v118
	v_fma_f32 v14, v8, v12, v16
	v_fma_f32 v15, v8, v13, v17
	v_fma_f32 v14, -v9, v13, v14
	v_fma_f32 v13, v9, v12, v15
	v_mov_b32_e32 v12, v14
	v_lshlrev_b32_e32 v16, 16, v119
	v_and_b32_e32 v17, 0xffff0000, v119
	v_fma_f32 v14, v8, v12, v16
	v_fma_f32 v15, v8, v13, v17
	v_fma_f32 v14, -v9, v13, v14
	v_fma_f32 v13, v9, v12, v15
	v_mov_b32_e32 v12, v14
	v_lshlrev_b32_e32 v16, 16, v120
	v_and_b32_e32 v17, 0xffff0000, v120
	v_fma_f32 v14, v8, v12, v16
	v_fma_f32 v15, v8, v13, v17
	v_fma_f32 v14, -v9, v13, v14
	v_fma_f32 v13, v9, v12, v15
	v_mov_b32_e32 v12, v14
	v_lshlrev_b32_e32 v16, 16, v121
	v_and_b32_e32 v17, 0xffff0000, v121
	v_fma_f32 v14, v8, v12, v16
	v_fma_f32 v15, v8, v13, v17
	v_fma_f32 v14, -v9, v13, v14
	v_fma_f32 v13, v9, v12, v15
	v_mov_b32_e32 v12, v14
	v_lshlrev_b32_e32 v16, 16, v122
	v_and_b32_e32 v17, 0xffff0000, v122
	v_fma_f32 v14, v8, v12, v16
	v_fma_f32 v15, v8, v13, v17
	v_fma_f32 v14, -v9, v13, v14
	v_fma_f32 v13, v9, v12, v15
	v_mov_b32_e32 v12, v14
	v_lshlrev_b32_e32 v16, 16, v123
	v_and_b32_e32 v17, 0xffff0000, v123
	v_fma_f32 v14, v8, v12, v16
	v_fma_f32 v15, v8, v13, v17
	v_fma_f32 v14, -v9, v13, v14
	v_fma_f32 v13, v9, v12, v15
	v_mov_b32_e32 v12, v14
	v_lshlrev_b32_e32 v16, 16, v124
	v_and_b32_e32 v17, 0xffff0000, v124
	v_fma_f32 v14, v8, v12, v16
	v_fma_f32 v15, v8, v13, v17
	v_fma_f32 v14, -v9, v13, v14
	v_fma_f32 v13, v9, v12, v15
	v_mov_b32_e32 v12, v14
	v_lshlrev_b32_e32 v16, 16, v125
	v_and_b32_e32 v17, 0xffff0000, v125
	v_fma_f32 v14, v8, v12, v16
	v_fma_f32 v15, v8, v13, v17
	v_fma_f32 v14, -v9, v13, v14
	v_fma_f32 v13, v9, v12, v15
	v_mov_b32_e32 v12, v14
	v_lshlrev_b32_e32 v16, 16, v126
	v_and_b32_e32 v17, 0xffff0000, v126
	v_fma_f32 v14, v8, v12, v16
	v_fma_f32 v15, v8, v13, v17
	v_fma_f32 v14, -v9, v13, v14
	v_fma_f32 v13, v9, v12, v15
	v_mov_b32_e32 v12, v14
	v_lshlrev_b32_e32 v16, 16, v127
	v_and_b32_e32 v17, 0xffff0000, v127
	v_fma_f32 v14, v8, v12, v16
	v_fma_f32 v15, v8, v13, v17
	v_fma_f32 v14, -v9, v13, v14
	v_fma_f32 v13, v9, v12, v15
	v_mov_b32_e32 v12, v14
	v_lshl_add_u32 v28, s0, 9, v23
	ds_write_b64 v28, v[12:13]
	s_waitcnt lgkmcnt(0)
	s_barrier
	v_mov_b32_e32 v18, 0
	v_mov_b32_e32 v19, 0
	s_cmp_le_u32 s0, 0
	s_cbranch_scc1 .Lscan_carry_done
	ds_read_b64 v[20:21], v23 offset:0
	s_waitcnt lgkmcnt(0)
	v_fma_f32 v14, v10, v18, v20
	v_fma_f32 v15, v10, v19, v21
	v_fma_f32 v14, -v11, v19, v14
	v_fma_f32 v19, v11, v18, v15
	v_mov_b32_e32 v18, v14
	s_cmp_le_u32 s0, 1
	s_cbranch_scc1 .Lscan_carry_done
	ds_read_b64 v[20:21], v23 offset:512
	s_waitcnt lgkmcnt(0)
	v_fma_f32 v14, v10, v18, v20
	v_fma_f32 v15, v10, v19, v21
	v_fma_f32 v14, -v11, v19, v14
	v_fma_f32 v19, v11, v18, v15
	v_mov_b32_e32 v18, v14
	s_cmp_le_u32 s0, 2
	s_cbranch_scc1 .Lscan_carry_done
	ds_read_b64 v[20:21], v23 offset:1024
	s_waitcnt lgkmcnt(0)
	v_fma_f32 v14, v10, v18, v20
	v_fma_f32 v15, v10, v19, v21
	v_fma_f32 v14, -v11, v19, v14
	v_fma_f32 v19, v11, v18, v15
	v_mov_b32_e32 v18, v14
	s_cmp_le_u32 s0, 3
	s_cbranch_scc1 .Lscan_carry_done
	ds_read_b64 v[20:21], v23 offset:1536
	s_waitcnt lgkmcnt(0)
	v_fma_f32 v14, v10, v18, v20
	v_fma_f32 v15, v10, v19, v21
	v_fma_f32 v14, -v11, v19, v14
	v_fma_f32 v19, v11, v18, v15
	v_mov_b32_e32 v18, v14
	s_cmp_le_u32 s0, 4
	s_cbranch_scc1 .Lscan_carry_done
	ds_read_b64 v[20:21], v23 offset:2048
	s_waitcnt lgkmcnt(0)
	v_fma_f32 v14, v10, v18, v20
	v_fma_f32 v15, v10, v19, v21
	v_fma_f32 v14, -v11, v19, v14
	v_fma_f32 v19, v11, v18, v15
	v_mov_b32_e32 v18, v14
	s_cmp_le_u32 s0, 5
	s_cbranch_scc1 .Lscan_carry_done
	ds_read_b64 v[20:21], v23 offset:2560
	s_waitcnt lgkmcnt(0)
	v_fma_f32 v14, v10, v18, v20
	v_fma_f32 v15, v10, v19, v21
	v_fma_f32 v14, -v11, v19, v14
	v_fma_f32 v19, v11, v18, v15
	v_mov_b32_e32 v18, v14
	s_cmp_le_u32 s0, 6
	s_cbranch_scc1 .Lscan_carry_done
	ds_read_b64 v[20:21], v23 offset:3072
	s_waitcnt lgkmcnt(0)
	v_fma_f32 v14, v10, v18, v20
	v_fma_f32 v15, v10, v19, v21
	v_fma_f32 v14, -v11, v19, v14
	v_fma_f32 v19, v11, v18, v15
	v_mov_b32_e32 v18, v14
.Lscan_carry_done:
	v_mov_b32_e32 v12, v18
	v_mov_b32_e32 v13, v19
	v_cvt_pk_bf16_f32 v29, v12, v13
	global_store_dword v22, v29, s[52:53] offset:0
	v_lshlrev_b32_e32 v16, 16, v64
	v_and_b32_e32 v17, 0xffff0000, v64
	v_fma_f32 v14, v8, v12, v16
	v_fma_f32 v15, v8, v13, v17
	v_fma_f32 v14, -v9, v13, v14
	v_fma_f32 v13, v9, v12, v15
	v_mov_b32_e32 v12, v14
	v_cvt_pk_bf16_f32 v29, v12, v13
	global_store_dword v22, v29, s[52:53] offset:1536
	s_add_u32 s52, s52, 0xc00
	s_addc_u32 s53, s53, 0
	v_lshlrev_b32_e32 v16, 16, v65
	v_and_b32_e32 v17, 0xffff0000, v65
	v_fma_f32 v14, v8, v12, v16
	v_fma_f32 v15, v8, v13, v17
	v_fma_f32 v14, -v9, v13, v14
	v_fma_f32 v13, v9, v12, v15
	v_mov_b32_e32 v12, v14
	v_cvt_pk_bf16_f32 v29, v12, v13
	global_store_dword v22, v29, s[52:53] offset:0
	v_lshlrev_b32_e32 v16, 16, v66
	v_and_b32_e32 v17, 0xffff0000, v66
	v_fma_f32 v14, v8, v12, v16
	v_fma_f32 v15, v8, v13, v17
	v_fma_f32 v14, -v9, v13, v14
	v_fma_f32 v13, v9, v12, v15
	v_mov_b32_e32 v12, v14
	v_cvt_pk_bf16_f32 v29, v12, v13
	global_store_dword v22, v29, s[52:53] offset:1536
	s_add_u32 s52, s52, 0xc00
	s_addc_u32 s53, s53, 0
	v_lshlrev_b32_e32 v16, 16, v67
	v_and_b32_e32 v17, 0xffff0000, v67
	v_fma_f32 v14, v8, v12, v16
	v_fma_f32 v15, v8, v13, v17
	v_fma_f32 v14, -v9, v13, v14
	v_fma_f32 v13, v9, v12, v15
	v_mov_b32_e32 v12, v14
	v_cvt_pk_bf16_f32 v29, v12, v13
	global_store_dword v22, v29, s[52:53] offset:0
	v_lshlrev_b32_e32 v16, 16, v68
	v_and_b32_e32 v17, 0xffff0000, v68
	v_fma_f32 v14, v8, v12, v16
; __device__ __forceinline__ float bf_lo(unsigned w) { return __uint_as_float(w << 16); }
; __device__ __forceinline__ float bf_hi(unsigned w) { return __uint_as_float(w & 0xffff0000u); }
; __device__ __forceinline__ unsigned pk2(float lo, float hi) { return pg8::cvt_pk_bf16(lo, hi); }
; __device__ __forceinline__ f32x2 cmul(f32x2 a, f32x2 b) { return (f32x2){a.x * b.x - a.y * b.y, a.x * b.y + a.y * b.x}; }
; __device__ __forceinline__ void phase_scan(const Args& a, LAS unsigned char* lds, int l, int G, const int bid, const int tid) {
;     ...
;         for (int i0 = 0; i0 < 64; i0 += 16) { unsigned eb[16];
; #pragma unroll
;             for (int k = 0; k < 16; ++k) eb[k] = ep[(size_t)(i0 + k) * 64];
; #pragma unroll
;             for (int k = 0; k < 16; ++k) { hp[(size_t)(i0 + k) * (ABP / 2)] = pk2(h.x, h.y); h = cmul(lam, h) + (f32x2){pg8::bf_lo(eb[k]), pg8::bf_hi(eb[k])}; } }
	v_fma_f32 v15, v8, v13, v17
	v_fma_f32 v14, -v9, v13, v14
	v_fma_f32 v13, v9, v12, v15
	v_mov_b32_e32 v12, v14
	v_cvt_pk_bf16_f32 v29, v12, v13
	global_store_dword v22, v29, s[52:53] offset:1536
	s_add_u32 s52, s52, 0xc00
	s_addc_u32 s53, s53, 0
	v_lshlrev_b32_e32 v16, 16, v69
	v_and_b32_e32 v17, 0xffff0000, v69
	v_fma_f32 v14, v8, v12, v16
	v_fma_f32 v15, v8, v13, v17
	v_fma_f32 v14, -v9, v13, v14
	v_fma_f32 v13, v9, v12, v15
	v_mov_b32_e32 v12, v14
	v_cvt_pk_bf16_f32 v29, v12, v13
	global_store_dword v22, v29, s[52:53] offset:0
	v_lshlrev_b32_e32 v16, 16, v70
	v_and_b32_e32 v17, 0xffff0000, v70
	v_fma_f32 v14, v8, v12, v16
	v_fma_f32 v15, v8, v13, v17
	v_fma_f32 v14, -v9, v13, v14
	v_fma_f32 v13, v9, v12, v15
	v_mov_b32_e32 v12, v14
	v_cvt_pk_bf16_f32 v29, v12, v13
	global_store_dword v22, v29, s[52:53] offset:1536
	s_add_u32 s52, s52, 0xc00
	s_addc_u32 s53, s53, 0
	v_lshlrev_b32_e32 v16, 16, v71
	v_and_b32_e32 v17, 0xffff0000, v71
	v_fma_f32 v14, v8, v12, v16
	v_fma_f32 v15, v8, v13, v17
	v_fma_f32 v14, -v9, v13, v14
	v_fma_f32 v13, v9, v12, v15
	v_mov_b32_e32 v12, v14
	v_cvt_pk_bf16_f32 v29, v12, v13
	global_store_dword v22, v29, s[52:53] offset:0
	v_lshlrev_b32_e32 v16, 16, v72
	v_and_b32_e32 v17, 0xffff0000, v72
	v_fma_f32 v14, v8, v12, v16
	v_fma_f32 v15, v8, v13, v17
	v_fma_f32 v14, -v9, v13, v14
	v_fma_f32 v13, v9, v12, v15
	v_mov_b32_e32 v12, v14
	v_cvt_pk_bf16_f32 v29, v12, v13
	global_store_dword v22, v29, s[52:53] offset:1536
	s_add_u32 s52, s52, 0xc00
	s_addc_u32 s53, s53, 0
	v_lshlrev_b32_e32 v16, 16, v73
	v_and_b32_e32 v17, 0xffff0000, v73
	v_fma_f32 v14, v8, v12, v16
	v_fma_f32 v15, v8, v13, v17
	v_fma_f32 v14, -v9, v13, v14
	v_fma_f32 v13, v9, v12, v15
	v_mov_b32_e32 v12, v14
	v_cvt_pk_bf16_f32 v29, v12, v13
	global_store_dword v22, v29, s[52:53] offset:0
	v_lshlrev_b32_e32 v16, 16, v74
	v_and_b32_e32 v17, 0xffff0000, v74
	v_fma_f32 v14, v8, v12, v16
	v_fma_f32 v15, v8, v13, v17
	v_fma_f32 v14, -v9, v13, v14
	v_fma_f32 v13, v9, v12, v15
	v_mov_b32_e32 v12, v14
	v_cvt_pk_bf16_f32 v29, v12, v13
	global_store_dword v22, v29, s[52:53] offset:1536
	s_add_u32 s52, s52, 0xc00
	s_addc_u32 s53, s53, 0
	v_lshlrev_b32_e32 v16, 16, v75
	v_and_b32_e32 v17, 0xffff0000, v75
	v_fma_f32 v14, v8, v12, v16
	v_fma_f32 v15, v8, v13, v17
	v_fma_f32 v14, -v9, v13, v14
	v_fma_f32 v13, v9, v12, v15
	v_mov_b32_e32 v12, v14
	v_cvt_pk_bf16_f32 v29, v12, v13
	global_store_dword v22, v29, s[52:53] offset:0
	v_lshlrev_b32_e32 v16, 16, v76
	v_and_b32_e32 v17, 0xffff0000, v76
	v_fma_f32 v14, v8, v12, v16
	v_fma_f32 v15, v8, v13, v17
	v_fma_f32 v14, -v9, v13, v14
	v_fma_f32 v13, v9, v12, v15
	v_mov_b32_e32 v12, v14
	v_cvt_pk_bf16_f32 v29, v12, v13
	global_store_dword v22, v29, s[52:53] offset:1536
	s_add_u32 s52, s52, 0xc00
	s_addc_u32 s53, s53, 0
	v_lshlrev_b32_e32 v16, 16, v77
	v_and_b32_e32 v17, 0xffff0000, v77
	v_fma_f32 v14, v8, v12, v16
	v_fma_f32 v15, v8, v13, v17
	v_fma_f32 v14, -v9, v13, v14
	v_fma_f32 v13, v9, v12, v15
	v_mov_b32_e32 v12, v14
	v_cvt_pk_bf16_f32 v29, v12, v13
	global_store_dword v22, v29, s[52:53] offset:0
	v_lshlrev_b32_e32 v16, 16, v78
	v_and_b32_e32 v17, 0xffff0000, v78
	v_fma_f32 v14, v8, v12, v16
	v_fma_f32 v15, v8, v13, v17
	v_fma_f32 v14, -v9, v13, v14
	v_fma_f32 v13, v9, v12, v15
	v_mov_b32_e32 v12, v14
	v_cvt_pk_bf16_f32 v29, v12, v13
	global_store_dword v22, v29, s[52:53] offset:1536
	s_add_u32 s52, s52, 0xc00
	s_addc_u32 s53, s53, 0
	v_lshlrev_b32_e32 v16, 16, v79
	v_and_b32_e32 v17, 0xffff0000, v79
	v_fma_f32 v14, v8, v12, v16
	v_fma_f32 v15, v8, v13, v17
	v_fma_f32 v14, -v9, v13, v14
	v_fma_f32 v13, v9, v12, v15
	v_mov_b32_e32 v12, v14
	v_cvt_pk_bf16_f32 v29, v12, v13
	global_store_dword v22, v29, s[52:53] offset:0
	v_lshlrev_b32_e32 v16, 16, v80
	v_and_b32_e32 v17, 0xffff0000, v80
	v_fma_f32 v14, v8, v12, v16
	v_fma_f32 v15, v8, v13, v17
	v_fma_f32 v14, -v9, v13, v14
	v_fma_f32 v13, v9, v12, v15
	v_mov_b32_e32 v12, v14
	v_cvt_pk_bf16_f32 v29, v12, v13
	global_store_dword v22, v29, s[52:53] offset:1536
	s_add_u32 s52, s52, 0xc00
	s_addc_u32 s53, s53, 0
	v_lshlrev_b32_e32 v16, 16, v81
	v_and_b32_e32 v17, 0xffff0000, v81
	v_fma_f32 v14, v8, v12, v16
	v_fma_f32 v15, v8, v13, v17
	v_fma_f32 v14, -v9, v13, v14
	v_fma_f32 v13, v9, v12, v15
	v_mov_b32_e32 v12, v14
	v_cvt_pk_bf16_f32 v29, v12, v13
	global_store_dword v22, v29, s[52:53] offset:0
	v_lshlrev_b32_e32 v16, 16, v82
	v_and_b32_e32 v17, 0xffff0000, v82
	v_fma_f32 v14, v8, v12, v16
	v_fma_f32 v15, v8, v13, v17
	v_fma_f32 v14, -v9, v13, v14
	v_fma_f32 v13, v9, v12, v15
	v_mov_b32_e32 v12, v14
	v_cvt_pk_bf16_f32 v29, v12, v13
	global_store_dword v22, v29, s[52:53] offset:1536
	s_add_u32 s52, s52, 0xc00
	s_addc_u32 s53, s53, 0
	v_lshlrev_b32_e32 v16, 16, v83
	v_and_b32_e32 v17, 0xffff0000, v83
	v_fma_f32 v14, v8, v12, v16
	v_fma_f32 v15, v8, v13, v17
	v_fma_f32 v14, -v9, v13, v14
	v_fma_f32 v13, v9, v12, v15
	v_mov_b32_e32 v12, v14
	v_cvt_pk_bf16_f32 v29, v12, v13
	global_store_dword v22, v29, s[52:53] offset:0
	v_lshlrev_b32_e32 v16, 16, v84
	v_and_b32_e32 v17, 0xffff0000, v84
	v_fma_f32 v14, v8, v12, v16
	v_fma_f32 v15, v8, v13, v17
	v_fma_f32 v14, -v9, v13, v14
	v_fma_f32 v13, v9, v12, v15
	v_mov_b32_e32 v12, v14
	v_cvt_pk_bf16_f32 v29, v12, v13
	global_store_dword v22, v29, s[52:53] offset:1536
	s_add_u32 s52, s52, 0xc00
	s_addc_u32 s53, s53, 0
	v_lshlrev_b32_e32 v16, 16, v85
	v_and_b32_e32 v17, 0xffff0000, v85
	v_fma_f32 v14, v8, v12, v16
	v_fma_f32 v15, v8, v13, v17
	v_fma_f32 v14, -v9, v13, v14
	v_fma_f32 v13, v9, v12, v15
	v_mov_b32_e32 v12, v14
	v_cvt_pk_bf16_f32 v29, v12, v13
	global_store_dword v22, v29, s[52:53] offset:0
	v_lshlrev_b32_e32 v16, 16, v86
; __device__ __forceinline__ float bf_lo(unsigned w) { return __uint_as_float(w << 16); }
; __device__ __forceinline__ float bf_hi(unsigned w) { return __uint_as_float(w & 0xffff0000u); }
; __device__ __forceinline__ unsigned pk2(float lo, float hi) { return pg8::cvt_pk_bf16(lo, hi); }
; __device__ __forceinline__ f32x2 cmul(f32x2 a, f32x2 b) { return (f32x2){a.x * b.x - a.y * b.y, a.x * b.y + a.y * b.x}; }
; __device__ __forceinline__ void phase_scan(const Args& a, LAS unsigned char* lds, int l, int G, const int bid, const int tid) {
;     ...
;         for (int i0 = 0; i0 < 64; i0 += 16) { unsigned eb[16];
; #pragma unroll
;             for (int k = 0; k < 16; ++k) eb[k] = ep[(size_t)(i0 + k) * 64];
; #pragma unroll
;             for (int k = 0; k < 16; ++k) { hp[(size_t)(i0 + k) * (ABP / 2)] = pk2(h.x, h.y); h = cmul(lam, h) + (f32x2){pg8::bf_lo(eb[k]), pg8::bf_hi(eb[k])}; } }
	v_and_b32_e32 v17, 0xffff0000, v86
	v_fma_f32 v14, v8, v12, v16
	v_fma_f32 v15, v8, v13, v17
	v_fma_f32 v14, -v9, v13, v14
	v_fma_f32 v13, v9, v12, v15
	v_mov_b32_e32 v12, v14
	v_cvt_pk_bf16_f32 v29, v12, v13
	global_store_dword v22, v29, s[52:53] offset:1536
	s_add_u32 s52, s52, 0xc00
	s_addc_u32 s53, s53, 0
	v_lshlrev_b32_e32 v16, 16, v87
	v_and_b32_e32 v17, 0xffff0000, v87
	v_fma_f32 v14, v8, v12, v16
	v_fma_f32 v15, v8, v13, v17
	v_fma_f32 v14, -v9, v13, v14
	v_fma_f32 v13, v9, v12, v15
	v_mov_b32_e32 v12, v14
	v_cvt_pk_bf16_f32 v29, v12, v13
	global_store_dword v22, v29, s[52:53] offset:0
	v_lshlrev_b32_e32 v16, 16, v88
	v_and_b32_e32 v17, 0xffff0000, v88
	v_fma_f32 v14, v8, v12, v16
	v_fma_f32 v15, v8, v13, v17
	v_fma_f32 v14, -v9, v13, v14
	v_fma_f32 v13, v9, v12, v15
	v_mov_b32_e32 v12, v14
	v_cvt_pk_bf16_f32 v29, v12, v13
	global_store_dword v22, v29, s[52:53] offset:1536
	s_add_u32 s52, s52, 0xc00
	s_addc_u32 s53, s53, 0
	v_lshlrev_b32_e32 v16, 16, v89
	v_and_b32_e32 v17, 0xffff0000, v89
	v_fma_f32 v14, v8, v12, v16
	v_fma_f32 v15, v8, v13, v17
	v_fma_f32 v14, -v9, v13, v14
	v_fma_f32 v13, v9, v12, v15
	v_mov_b32_e32 v12, v14
	v_cvt_pk_bf16_f32 v29, v12, v13
	global_store_dword v22, v29, s[52:53] offset:0
	v_lshlrev_b32_e32 v16, 16, v90
	v_and_b32_e32 v17, 0xffff0000, v90
	v_fma_f32 v14, v8, v12, v16
	v_fma_f32 v15, v8, v13, v17
	v_fma_f32 v14, -v9, v13, v14
	v_fma_f32 v13, v9, v12, v15
	v_mov_b32_e32 v12, v14
	v_cvt_pk_bf16_f32 v29, v12, v13
	global_store_dword v22, v29, s[52:53] offset:1536
	s_add_u32 s52, s52, 0xc00
	s_addc_u32 s53, s53, 0
	v_lshlrev_b32_e32 v16, 16, v91
	v_and_b32_e32 v17, 0xffff0000, v91
	v_fma_f32 v14, v8, v12, v16
	v_fma_f32 v15, v8, v13, v17
	v_fma_f32 v14, -v9, v13, v14
	v_fma_f32 v13, v9, v12, v15
	v_mov_b32_e32 v12, v14
	v_cvt_pk_bf16_f32 v29, v12, v13
	global_store_dword v22, v29, s[52:53] offset:0
	v_lshlrev_b32_e32 v16, 16, v92
	v_and_b32_e32 v17, 0xffff0000, v92
	v_fma_f32 v14, v8, v12, v16
	v_fma_f32 v15, v8, v13, v17
	v_fma_f32 v14, -v9, v13, v14
	v_fma_f32 v13, v9, v12, v15
	v_mov_b32_e32 v12, v14
	v_cvt_pk_bf16_f32 v29, v12, v13
	global_store_dword v22, v29, s[52:53] offset:1536
	s_add_u32 s52, s52, 0xc00
	s_addc_u32 s53, s53, 0
	v_lshlrev_b32_e32 v16, 16, v93
	v_and_b32_e32 v17, 0xffff0000, v93
	v_fma_f32 v14, v8, v12, v16
	v_fma_f32 v15, v8, v13, v17
	v_fma_f32 v14, -v9, v13, v14
	v_fma_f32 v13, v9, v12, v15
	v_mov_b32_e32 v12, v14
	v_cvt_pk_bf16_f32 v29, v12, v13
	global_store_dword v22, v29, s[52:53] offset:0
	v_lshlrev_b32_e32 v16, 16, v94
	v_and_b32_e32 v17, 0xffff0000, v94
	v_fma_f32 v14, v8, v12, v16
	v_fma_f32 v15, v8, v13, v17
	v_fma_f32 v14, -v9, v13, v14
	v_fma_f32 v13, v9, v12, v15
	v_mov_b32_e32 v12, v14
	v_cvt_pk_bf16_f32 v29, v12, v13
	global_store_dword v22, v29, s[52:53] offset:1536
	s_add_u32 s52, s52, 0xc00
	s_addc_u32 s53, s53, 0
	v_lshlrev_b32_e32 v16, 16, v95
	v_and_b32_e32 v17, 0xffff0000, v95
	v_fma_f32 v14, v8, v12, v16
	v_fma_f32 v15, v8, v13, v17
	v_fma_f32 v14, -v9, v13, v14
	v_fma_f32 v13, v9, v12, v15
	v_mov_b32_e32 v12, v14
	v_cvt_pk_bf16_f32 v29, v12, v13
	global_store_dword v22, v29, s[52:53] offset:0
	v_lshlrev_b32_e32 v16, 16, v96
	v_and_b32_e32 v17, 0xffff0000, v96
	v_fma_f32 v14, v8, v12, v16
	v_fma_f32 v15, v8, v13, v17
	v_fma_f32 v14, -v9, v13, v14
	v_fma_f32 v13, v9, v12, v15
	v_mov_b32_e32 v12, v14
	v_cvt_pk_bf16_f32 v29, v12, v13
	global_store_dword v22, v29, s[52:53] offset:1536
	s_add_u32 s52, s52, 0xc00
	s_addc_u32 s53, s53, 0
	v_lshlrev_b32_e32 v16, 16, v97
	v_and_b32_e32 v17, 0xffff0000, v97
	v_fma_f32 v14, v8, v12, v16
	v_fma_f32 v15, v8, v13, v17
	v_fma_f32 v14, -v9, v13, v14
	v_fma_f32 v13, v9, v12, v15
	v_mov_b32_e32 v12, v14
	v_cvt_pk_bf16_f32 v29, v12, v13
	global_store_dword v22, v29, s[52:53] offset:0
	v_lshlrev_b32_e32 v16, 16, v98
	v_and_b32_e32 v17, 0xffff0000, v98
	v_fma_f32 v14, v8, v12, v16
	v_fma_f32 v15, v8, v13, v17
	v_fma_f32 v14, -v9, v13, v14
	v_fma_f32 v13, v9, v12, v15
	v_mov_b32_e32 v12, v14
	v_cvt_pk_bf16_f32 v29, v12, v13
	global_store_dword v22, v29, s[52:53] offset:1536
	s_add_u32 s52, s52, 0xc00
	s_addc_u32 s53, s53, 0
	v_lshlrev_b32_e32 v16, 16, v99
	v_and_b32_e32 v17, 0xffff0000, v99
	v_fma_f32 v14, v8, v12, v16
	v_fma_f32 v15, v8, v13, v17
	v_fma_f32 v14, -v9, v13, v14
	v_fma_f32 v13, v9, v12, v15
	v_mov_b32_e32 v12, v14
	v_cvt_pk_bf16_f32 v29, v12, v13
	global_store_dword v22, v29, s[52:53] offset:0
	v_lshlrev_b32_e32 v16, 16, v100
	v_and_b32_e32 v17, 0xffff0000, v100
	v_fma_f32 v14, v8, v12, v16
	v_fma_f32 v15, v8, v13, v17
	v_fma_f32 v14, -v9, v13, v14
	v_fma_f32 v13, v9, v12, v15
	v_mov_b32_e32 v12, v14
	v_cvt_pk_bf16_f32 v29, v12, v13
	global_store_dword v22, v29, s[52:53] offset:1536
	s_add_u32 s52, s52, 0xc00
	s_addc_u32 s53, s53, 0
	v_lshlrev_b32_e32 v16, 16, v101
	v_and_b32_e32 v17, 0xffff0000, v101
	v_fma_f32 v14, v8, v12, v16
	v_fma_f32 v15, v8, v13, v17
	v_fma_f32 v14, -v9, v13, v14
	v_fma_f32 v13, v9, v12, v15
	v_mov_b32_e32 v12, v14
	v_cvt_pk_bf16_f32 v29, v12, v13
	global_store_dword v22, v29, s[52:53] offset:0
	v_lshlrev_b32_e32 v16, 16, v102
	v_and_b32_e32 v17, 0xffff0000, v102
	v_fma_f32 v14, v8, v12, v16
	v_fma_f32 v15, v8, v13, v17
	v_fma_f32 v14, -v9, v13, v14
	v_fma_f32 v13, v9, v12, v15
	v_mov_b32_e32 v12, v14
	v_cvt_pk_bf16_f32 v29, v12, v13
	global_store_dword v22, v29, s[52:53] offset:1536
	s_add_u32 s52, s52, 0xc00
	s_addc_u32 s53, s53, 0
	v_lshlrev_b32_e32 v16, 16, v103
	v_and_b32_e32 v17, 0xffff0000, v103
	v_fma_f32 v14, v8, v12, v16
	v_fma_f32 v15, v8, v13, v17
	v_fma_f32 v14, -v9, v13, v14
	v_fma_f32 v13, v9, v12, v15
	v_mov_b32_e32 v12, v14
	v_cvt_pk_bf16_f32 v29, v12, v13
	global_store_dword v22, v29, s[52:53] offset:0
	v_lshlrev_b32_e32 v16, 16, v104
	v_and_b32_e32 v17, 0xffff0000, v104
	v_fma_f32 v14, v8, v12, v16
	v_fma_f32 v15, v8, v13, v17
	v_fma_f32 v14, -v9, v13, v14
	v_fma_f32 v13, v9, v12, v15
	v_mov_b32_e32 v12, v14
	s_waitcnt vmcnt(20)
; __device__ __forceinline__ float bf_lo(unsigned w) { return __uint_as_float(w << 16); }
; __device__ __forceinline__ float bf_hi(unsigned w) { return __uint_as_float(w & 0xffff0000u); }
; __device__ __forceinline__ unsigned pk2(float lo, float hi) { return pg8::cvt_pk_bf16(lo, hi); }
; __device__ __forceinline__ f32x2 cmul(f32x2 a, f32x2 b) { return (f32x2){a.x * b.x - a.y * b.y, a.x * b.y + a.y * b.x}; }
; __device__ __forceinline__ void phase_scan(const Args& a, LAS unsigned char* lds, int l, int G, const int bid, const int tid) {
;     ...
;         for (int i0 = 0; i0 < 64; i0 += 16) { unsigned eb[16];
; #pragma unroll
;             for (int k = 0; k < 16; ++k) eb[k] = ep[(size_t)(i0 + k) * 64];
; #pragma unroll
;             for (int k = 0; k < 16; ++k) { hp[(size_t)(i0 + k) * (ABP / 2)] = pk2(h.x, h.y); h = cmul(lam, h) + (f32x2){pg8::bf_lo(eb[k]), pg8::bf_hi(eb[k])}; } }
	v_cvt_pk_bf16_f32 v29, v12, v13
	global_store_dword v22, v29, s[52:53] offset:1536
	s_add_u32 s52, s52, 0xc00
	s_addc_u32 s53, s53, 0
	v_lshlrev_b32_e32 v16, 16, v105
	v_and_b32_e32 v17, 0xffff0000, v105
	v_fma_f32 v14, v8, v12, v16
	v_fma_f32 v15, v8, v13, v17
	v_fma_f32 v14, -v9, v13, v14
	v_fma_f32 v13, v9, v12, v15
	v_mov_b32_e32 v12, v14
	v_cvt_pk_bf16_f32 v29, v12, v13
	global_store_dword v22, v29, s[52:53] offset:0
	v_lshlrev_b32_e32 v16, 16, v106
	v_and_b32_e32 v17, 0xffff0000, v106
	v_fma_f32 v14, v8, v12, v16
	v_fma_f32 v15, v8, v13, v17
	v_fma_f32 v14, -v9, v13, v14
	v_fma_f32 v13, v9, v12, v15
	v_mov_b32_e32 v12, v14
	v_cvt_pk_bf16_f32 v29, v12, v13
	global_store_dword v22, v29, s[52:53] offset:1536
	s_add_u32 s52, s52, 0xc00
	s_addc_u32 s53, s53, 0
	v_lshlrev_b32_e32 v16, 16, v107
	v_and_b32_e32 v17, 0xffff0000, v107
	v_fma_f32 v14, v8, v12, v16
	v_fma_f32 v15, v8, v13, v17
	v_fma_f32 v14, -v9, v13, v14
	v_fma_f32 v13, v9, v12, v15
	v_mov_b32_e32 v12, v14
	v_cvt_pk_bf16_f32 v29, v12, v13
	global_store_dword v22, v29, s[52:53] offset:0
	v_lshlrev_b32_e32 v16, 16, v108
	v_and_b32_e32 v17, 0xffff0000, v108
	v_fma_f32 v14, v8, v12, v16
	v_fma_f32 v15, v8, v13, v17
	v_fma_f32 v14, -v9, v13, v14
	v_fma_f32 v13, v9, v12, v15
	v_mov_b32_e32 v12, v14
	v_cvt_pk_bf16_f32 v29, v12, v13
	global_store_dword v22, v29, s[52:53] offset:1536
	s_add_u32 s52, s52, 0xc00
	s_addc_u32 s53, s53, 0
	v_lshlrev_b32_e32 v16, 16, v109
	v_and_b32_e32 v17, 0xffff0000, v109
	v_fma_f32 v14, v8, v12, v16
	v_fma_f32 v15, v8, v13, v17
	v_fma_f32 v14, -v9, v13, v14
	v_fma_f32 v13, v9, v12, v15
	v_mov_b32_e32 v12, v14
	v_cvt_pk_bf16_f32 v29, v12, v13
	global_store_dword v22, v29, s[52:53] offset:0
	v_lshlrev_b32_e32 v16, 16, v110
	v_and_b32_e32 v17, 0xffff0000, v110
	v_fma_f32 v14, v8, v12, v16
	v_fma_f32 v15, v8, v13, v17
	v_fma_f32 v14, -v9, v13, v14
	v_fma_f32 v13, v9, v12, v15
	v_mov_b32_e32 v12, v14
	v_cvt_pk_bf16_f32 v29, v12, v13
	global_store_dword v22, v29, s[52:53] offset:1536
	s_add_u32 s52, s52, 0xc00
	s_addc_u32 s53, s53, 0
	v_lshlrev_b32_e32 v16, 16, v111
	v_and_b32_e32 v17, 0xffff0000, v111
	v_fma_f32 v14, v8, v12, v16
	v_fma_f32 v15, v8, v13, v17
	v_fma_f32 v14, -v9, v13, v14
	v_fma_f32 v13, v9, v12, v15
	v_mov_b32_e32 v12, v14
	v_cvt_pk_bf16_f32 v29, v12, v13
	global_store_dword v22, v29, s[52:53] offset:0
	v_lshlrev_b32_e32 v16, 16, v112
	v_and_b32_e32 v17, 0xffff0000, v112
	v_fma_f32 v14, v8, v12, v16
	v_fma_f32 v15, v8, v13, v17
	v_fma_f32 v14, -v9, v13, v14
	v_fma_f32 v13, v9, v12, v15
	v_mov_b32_e32 v12, v14
	v_cvt_pk_bf16_f32 v29, v12, v13
	global_store_dword v22, v29, s[52:53] offset:1536
	s_add_u32 s52, s52, 0xc00
	s_addc_u32 s53, s53, 0
	v_lshlrev_b32_e32 v16, 16, v113
	v_and_b32_e32 v17, 0xffff0000, v113
	v_fma_f32 v14, v8, v12, v16
	v_fma_f32 v15, v8, v13, v17
	v_fma_f32 v14, -v9, v13, v14
	v_fma_f32 v13, v9, v12, v15
	v_mov_b32_e32 v12, v14
	v_cvt_pk_bf16_f32 v29, v12, v13
	global_store_dword v22, v29, s[52:53] offset:0
	v_lshlrev_b32_e32 v16, 16, v114
	v_and_b32_e32 v17, 0xffff0000, v114
	v_fma_f32 v14, v8, v12, v16
	v_fma_f32 v15, v8, v13, v17
	v_fma_f32 v14, -v9, v13, v14
	v_fma_f32 v13, v9, v12, v15
	v_mov_b32_e32 v12, v14
	v_cvt_pk_bf16_f32 v29, v12, v13
	global_store_dword v22, v29, s[52:53] offset:1536
	s_add_u32 s52, s52, 0xc00
	s_addc_u32 s53, s53, 0
	v_lshlrev_b32_e32 v16, 16, v115
	v_and_b32_e32 v17, 0xffff0000, v115
	v_fma_f32 v14, v8, v12, v16
	v_fma_f32 v15, v8, v13, v17
	v_fma_f32 v14, -v9, v13, v14
	v_fma_f32 v13, v9, v12, v15
	v_mov_b32_e32 v12, v14
	v_cvt_pk_bf16_f32 v29, v12, v13
	global_store_dword v22, v29, s[52:53] offset:0
	v_lshlrev_b32_e32 v16, 16, v116
	v_and_b32_e32 v17, 0xffff0000, v116
	v_fma_f32 v14, v8, v12, v16
	v_fma_f32 v15, v8, v13, v17
	v_fma_f32 v14, -v9, v13, v14
	v_fma_f32 v13, v9, v12, v15
	v_mov_b32_e32 v12, v14
	v_cvt_pk_bf16_f32 v29, v12, v13
	global_store_dword v22, v29, s[52:53] offset:1536
; __device__ __forceinline__ float bf_lo(unsigned w) { return __uint_as_float(w << 16); }
; __device__ __forceinline__ float bf_hi(unsigned w) { return __uint_as_float(w & 0xffff0000u); }
; __device__ __forceinline__ unsigned pk2(float lo, float hi) { return pg8::cvt_pk_bf16(lo, hi); }
; __device__ __forceinline__ f32x2 cmul(f32x2 a, f32x2 b) { return (f32x2){a.x * b.x - a.y * b.y, a.x * b.y + a.y * b.x}; }
; __device__ __forceinline__ void phase_scan(const Args& a, LAS unsigned char* lds, int l, int G, const int bid, const int tid) {
;     ...
;         for (int i0 = 0; i0 < 64; i0 += 16) { unsigned eb[16];
; #pragma unroll
;             for (int k = 0; k < 16; ++k) eb[k] = ep[(size_t)(i0 + k) * 64];
; #pragma unroll
;             for (int k = 0; k < 16; ++k) { hp[(size_t)(i0 + k) * (ABP / 2)] = pk2(h.x, h.y); h = cmul(lam, h) + (f32x2){pg8::bf_lo(eb[k]), pg8::bf_hi(eb[k])}; } }
;         if (wave == 7) { a.out[O_PRE + (size_t)((l * PB_ + seq) * NG + g) * NP + p] = h.x; a.out[O_PIM + (size_t)((l * PB_ + seq) * NG + g) * NP + p] = h.y; }
	s_add_u32 s52, s52, 0xc00
	s_addc_u32 s53, s53, 0
	v_lshlrev_b32_e32 v16, 16, v117
	v_and_b32_e32 v17, 0xffff0000, v117
	v_fma_f32 v14, v8, v12, v16
	v_fma_f32 v15, v8, v13, v17
	v_fma_f32 v14, -v9, v13, v14
	v_fma_f32 v13, v9, v12, v15
	v_mov_b32_e32 v12, v14
	v_cvt_pk_bf16_f32 v29, v12, v13
	global_store_dword v22, v29, s[52:53] offset:0
	v_lshlrev_b32_e32 v16, 16, v118
	v_and_b32_e32 v17, 0xffff0000, v118
	v_fma_f32 v14, v8, v12, v16
	v_fma_f32 v15, v8, v13, v17
	v_fma_f32 v14, -v9, v13, v14
	v_fma_f32 v13, v9, v12, v15
	v_mov_b32_e32 v12, v14
	v_cvt_pk_bf16_f32 v29, v12, v13
	global_store_dword v22, v29, s[52:53] offset:1536
	s_add_u32 s52, s52, 0xc00
	s_addc_u32 s53, s53, 0
	v_lshlrev_b32_e32 v16, 16, v119
	v_and_b32_e32 v17, 0xffff0000, v119
	v_fma_f32 v14, v8, v12, v16
	v_fma_f32 v15, v8, v13, v17
	v_fma_f32 v14, -v9, v13, v14
	v_fma_f32 v13, v9, v12, v15
	v_mov_b32_e32 v12, v14
	v_cvt_pk_bf16_f32 v29, v12, v13
	global_store_dword v22, v29, s[52:53] offset:0
	v_lshlrev_b32_e32 v16, 16, v120
	v_and_b32_e32 v17, 0xffff0000, v120
	v_fma_f32 v14, v8, v12, v16
	v_fma_f32 v15, v8, v13, v17
	v_fma_f32 v14, -v9, v13, v14
	v_fma_f32 v13, v9, v12, v15
	v_mov_b32_e32 v12, v14
	v_cvt_pk_bf16_f32 v29, v12, v13
	global_store_dword v22, v29, s[52:53] offset:1536
	s_add_u32 s52, s52, 0xc00
	s_addc_u32 s53, s53, 0
	v_lshlrev_b32_e32 v16, 16, v121
	v_and_b32_e32 v17, 0xffff0000, v121
	v_fma_f32 v14, v8, v12, v16
	v_fma_f32 v15, v8, v13, v17
	v_fma_f32 v14, -v9, v13, v14
	v_fma_f32 v13, v9, v12, v15
	v_mov_b32_e32 v12, v14
	v_cvt_pk_bf16_f32 v29, v12, v13
	global_store_dword v22, v29, s[52:53] offset:0
	v_lshlrev_b32_e32 v16, 16, v122
	v_and_b32_e32 v17, 0xffff0000, v122
	v_fma_f32 v14, v8, v12, v16
	v_fma_f32 v15, v8, v13, v17
	v_fma_f32 v14, -v9, v13, v14
	v_fma_f32 v13, v9, v12, v15
	v_mov_b32_e32 v12, v14
	v_cvt_pk_bf16_f32 v29, v12, v13
	global_store_dword v22, v29, s[52:53] offset:1536
	s_add_u32 s52, s52, 0xc00
	s_addc_u32 s53, s53, 0
	v_lshlrev_b32_e32 v16, 16, v123
	v_and_b32_e32 v17, 0xffff0000, v123
	v_fma_f32 v14, v8, v12, v16
	v_fma_f32 v15, v8, v13, v17
	v_fma_f32 v14, -v9, v13, v14
	v_fma_f32 v13, v9, v12, v15
	v_mov_b32_e32 v12, v14
	v_cvt_pk_bf16_f32 v29, v12, v13
	global_store_dword v22, v29, s[52:53] offset:0
	v_lshlrev_b32_e32 v16, 16, v124
	v_and_b32_e32 v17, 0xffff0000, v124
	v_fma_f32 v14, v8, v12, v16
	v_fma_f32 v15, v8, v13, v17
	v_fma_f32 v14, -v9, v13, v14
	v_fma_f32 v13, v9, v12, v15
	v_mov_b32_e32 v12, v14
	v_cvt_pk_bf16_f32 v29, v12, v13
	global_store_dword v22, v29, s[52:53] offset:1536
	s_add_u32 s52, s52, 0xc00
	s_addc_u32 s53, s53, 0
	v_lshlrev_b32_e32 v16, 16, v125
	v_and_b32_e32 v17, 0xffff0000, v125
	v_fma_f32 v14, v8, v12, v16
	v_fma_f32 v15, v8, v13, v17
	v_fma_f32 v14, -v9, v13, v14
	v_fma_f32 v13, v9, v12, v15
	v_mov_b32_e32 v12, v14
	v_cvt_pk_bf16_f32 v29, v12, v13
	global_store_dword v22, v29, s[52:53] offset:0
	v_lshlrev_b32_e32 v16, 16, v126
	v_and_b32_e32 v17, 0xffff0000, v126
	v_fma_f32 v14, v8, v12, v16
	v_fma_f32 v15, v8, v13, v17
	v_fma_f32 v14, -v9, v13, v14
	v_fma_f32 v13, v9, v12, v15
	v_mov_b32_e32 v12, v14
	v_cvt_pk_bf16_f32 v29, v12, v13
	global_store_dword v22, v29, s[52:53] offset:1536
	s_add_u32 s52, s52, 0xc00
	s_addc_u32 s53, s53, 0
	v_lshlrev_b32_e32 v16, 16, v127
	v_and_b32_e32 v17, 0xffff0000, v127
	v_fma_f32 v14, v8, v12, v16
	v_fma_f32 v15, v8, v13, v17
	v_fma_f32 v14, -v9, v13, v14
	v_fma_f32 v13, v9, v12, v15
	v_mov_b32_e32 v12, v14
	s_cmp_lg_u32 s0, 7
	s_cbranch_scc1 .Lscan_pair_done
	v_readlane_b32 s8, v253, 44
	v_readlane_b32 s9, v253, 45
	s_add_u32 s1, s11, s12
	s_lshl_b32 s1, s1, 8
	s_add_u32 s8, s8, s1
	s_addc_u32 s9, s9, 0
	s_add_u32 s8, s8, 0x10800000
	s_addc_u32 s9, s9, 0
	global_store_dword v22, v12, s[8:9]
	s_add_u32 s8, s8, 0x20000
	s_addc_u32 s9, s9, 0
	global_store_dword v22, v13, s[8:9]
.Lscan_pair_done:
	s_branch .Lscan_next
.LBB0_488:
	s_mov_b64 s[4:5], 0
	s_branch .LBB0_577
